# v83 + the same peeled C=0 first iteration (no accumulator zero-init) for the P3 and P6 main loops
# speedup vs baseline: 1.0109x; 1.0015x over previous
.LBB0_258:
	s_ashr_i32 s75, s74, 31
	s_lshl_b64 s[14:15], s[74:75], 19
	s_add_u32 s76, s28, s14
	s_addc_u32 s77, s29, s15
	s_and_b64 s[14:15], s[10:11], exec
	s_cselect_b32 s1, s77, s13
	s_cselect_b32 s20, s76, s12
	s_ashr_i32 s73, s72, 31
	s_lshl_b64 s[14:15], s[72:73], 19
	s_add_u32 s78, s22, s14
	s_addc_u32 s79, s23, s15
	s_and_b64 s[14:15], s[10:11], exec
	s_cselect_b32 s21, s79, s17
	s_cselect_b32 s56, s78, s16
	s_add_u32 s12, s12, 0x40080
	s_addc_u32 s13, s13, 0
	s_add_u32 s14, s16, 0x100
	s_addc_u32 s15, s17, 0
	s_mov_b32 s57, -2
	s_waitcnt lgkmcnt(0)
	ds_read_b128 v[128:131], v171
	ds_read_b128 v[132:135], v171 offset:1024
	ds_read_b128 v[136:139], v171 offset:2048
	ds_read_b128 v[156:159], v171 offset:3072
	ds_read_b128 v[160:163], v172
	ds_read_b128 v[164:167], v172 offset:1024
	ds_read_b128 v[176:179], v172 offset:2048
	ds_read_b128 v[180:183], v172 offset:3072
	s_add_u32 s16, s12, 0xfffc0080
	s_addc_u32 s17, s13, -1
	s_cmp_eq_u32 s57, 12
	s_cselect_b32 s19, s1, s17
	s_cselect_b32 s18, s20, s16
	s_cselect_b32 s17, s21, s15
	s_cselect_b32 s16, s56, s14
	v_lshl_add_u64 v[222:223], s[12:13], 0, v[148:149]
	s_add_i32 m0, s83, 0xc000
	ds_read_b128 v[184:187], v173
	ds_read_b128 v[188:191], v173 offset:1024
	ds_read_b128 v[192:195], v173 offset:2048
	ds_read_b128 v[198:201], v173 offset:3072
	ds_read_b128 v[206:209], v173 offset:4096
	ds_read_b128 v[210:213], v173 offset:5120
	ds_read_b128 v[214:217], v173 offset:6144
	ds_read_b128 v[218:221], v173 offset:7168
	global_load_lds_dwordx4 v[222:223], off
	v_lshl_add_u64 v[222:223], s[12:13], 0, v[150:151]
	s_add_i32 m0, s83, 0xe000
	s_nop 0
	global_load_lds_dwordx4 v[222:223], off
	s_waitcnt vmcnt(8)
	s_waitcnt lgkmcnt(0)
	s_barrier
	s_setprio 1
	s_waitcnt lgkmcnt(0)
	v_mfma_f32_16x16x32_bf16 v[124:127], v[128:131], v[184:187], 0
	v_mfma_f32_16x16x32_bf16 v[120:123], v[136:139], v[184:187], 0
	v_mfma_f32_16x16x32_bf16 v[108:111], v[128:131], v[192:195], 0
	v_mfma_f32_16x16x32_bf16 v[104:107], v[136:139], v[192:195], 0
	v_mfma_f32_16x16x32_bf16 v[92:95], v[128:131], v[206:209], 0
	v_mfma_f32_16x16x32_bf16 v[88:91], v[136:139], v[206:209], 0
	v_mfma_f32_16x16x32_bf16 v[76:79], v[128:131], v[214:217], 0
	v_mfma_f32_16x16x32_bf16 v[72:75], v[136:139], v[214:217], 0
	v_mfma_f32_16x16x32_bf16 v[124:127], v[132:135], v[188:191], v[124:127]
	v_mfma_f32_16x16x32_bf16 v[120:123], v[156:159], v[188:191], v[120:123]
	v_mfma_f32_16x16x32_bf16 v[108:111], v[132:135], v[198:201], v[108:111]
	v_mfma_f32_16x16x32_bf16 v[104:107], v[156:159], v[198:201], v[104:107]
	v_mfma_f32_16x16x32_bf16 v[92:95], v[132:135], v[210:213], v[92:95]
	v_mfma_f32_16x16x32_bf16 v[88:91], v[156:159], v[210:213], v[88:91]
	v_mfma_f32_16x16x32_bf16 v[76:79], v[132:135], v[218:221], v[76:79]
	v_mfma_f32_16x16x32_bf16 v[72:75], v[156:159], v[218:221], v[72:75]
	s_setprio 0
	s_setprio 1
	v_mfma_f32_16x16x32_bf16 v[116:119], v[160:163], v[184:187], 0
	v_mfma_f32_16x16x32_bf16 v[112:115], v[176:179], v[184:187], 0
	v_mfma_f32_16x16x32_bf16 v[100:103], v[160:163], v[192:195], 0
	v_mfma_f32_16x16x32_bf16 v[96:99], v[176:179], v[192:195], 0
	v_mfma_f32_16x16x32_bf16 v[84:87], v[160:163], v[206:209], 0
	v_mfma_f32_16x16x32_bf16 v[80:83], v[176:179], v[206:209], 0
	v_mfma_f32_16x16x32_bf16 v[68:71], v[160:163], v[214:217], 0
	v_mfma_f32_16x16x32_bf16 v[64:67], v[176:179], v[214:217], 0
	v_mfma_f32_16x16x32_bf16 v[116:119], v[164:167], v[188:191], v[116:119]
	v_mfma_f32_16x16x32_bf16 v[112:115], v[180:183], v[188:191], v[112:115]
	v_mfma_f32_16x16x32_bf16 v[100:103], v[164:167], v[198:201], v[100:103]
	v_mfma_f32_16x16x32_bf16 v[96:99], v[180:183], v[198:201], v[96:99]
	v_mfma_f32_16x16x32_bf16 v[84:87], v[164:167], v[210:213], v[84:87]
	v_mfma_f32_16x16x32_bf16 v[80:83], v[180:183], v[210:213], v[80:83]
	v_mfma_f32_16x16x32_bf16 v[68:71], v[164:167], v[218:221], v[68:71]
	v_mfma_f32_16x16x32_bf16 v[64:67], v[180:183], v[218:221], v[64:67]
	s_setprio 0
	s_barrier
	s_add_i32 s33, s93, s82
	v_lshl_add_u64 v[222:223], s[16:17], 0, v[142:143]
	s_mov_b32 m0, s33
	ds_read_b128 v[184:187], v173 offset:16384
	ds_read_b128 v[188:191], v173 offset:17408
	ds_read_b128 v[192:195], v173 offset:18432
	ds_read_b128 v[198:201], v173 offset:19456
	ds_read_b128 v[206:209], v173 offset:20480
	ds_read_b128 v[210:213], v173 offset:21504
	ds_read_b128 v[214:217], v173 offset:22528
	ds_read_b128 v[218:221], v173 offset:23552
	global_load_lds_dwordx4 v[222:223], off
	s_add_i32 m0, s33, 0x2000
	s_add_u32 s44, s16, 0x40000
	v_lshl_add_u64 v[224:225], s[16:17], 0, v[146:147]
	s_addc_u32 s45, s17, 0
	s_add_i32 s33, s94, s82
	global_load_lds_dwordx4 v[224:225], off
	v_lshl_add_u64 v[226:227], s[44:45], 0, v[142:143]
	s_mov_b32 m0, s33
	v_lshl_add_u64 v[228:229], s[18:19], 0, v[144:145]
	global_load_lds_dwordx4 v[226:227], off
	v_lshl_add_u64 v[226:227], s[44:45], 0, v[146:147]
	s_add_i32 m0, s33, 0x2000
	s_nop 0
	global_load_lds_dwordx4 v[226:227], off
	v_lshl_add_u64 v[226:227], s[18:19], 0, v[140:141]
	s_mov_b32 m0, s83
	s_nop 0
	global_load_lds_dwordx4 v[226:227], off
	s_mov_b32 m0, s84
	s_nop 0
	global_load_lds_dwordx4 v[228:229], off
	s_waitcnt vmcnt(8)
	s_waitcnt lgkmcnt(0)
	s_barrier
	s_setprio 1
	s_waitcnt lgkmcnt(0)
	v_mfma_f32_16x16x32_bf16 v[60:63], v[128:131], v[184:187], 0
	v_mfma_f32_16x16x32_bf16 v[56:59], v[136:139], v[184:187], 0
	v_mfma_f32_16x16x32_bf16 v[44:47], v[128:131], v[192:195], 0
	v_mfma_f32_16x16x32_bf16 v[40:43], v[136:139], v[192:195], 0
	v_mfma_f32_16x16x32_bf16 v[28:31], v[128:131], v[206:209], 0
	v_mfma_f32_16x16x32_bf16 v[24:27], v[136:139], v[206:209], 0
	v_mfma_f32_16x16x32_bf16 v[12:15], v[128:131], v[214:217], 0
	v_mfma_f32_16x16x32_bf16 v[8:11], v[136:139], v[214:217], 0
	v_mfma_f32_16x16x32_bf16 v[60:63], v[132:135], v[188:191], v[60:63]
	v_mfma_f32_16x16x32_bf16 v[56:59], v[156:159], v[188:191], v[56:59]
	v_mfma_f32_16x16x32_bf16 v[44:47], v[132:135], v[198:201], v[44:47]
	v_mfma_f32_16x16x32_bf16 v[40:43], v[156:159], v[198:201], v[40:43]
	v_mfma_f32_16x16x32_bf16 v[28:31], v[132:135], v[210:213], v[28:31]
	v_mfma_f32_16x16x32_bf16 v[24:27], v[156:159], v[210:213], v[24:27]
	v_mfma_f32_16x16x32_bf16 v[12:15], v[132:135], v[218:221], v[12:15]
	v_mfma_f32_16x16x32_bf16 v[8:11], v[156:159], v[218:221], v[8:11]
	s_setprio 0
	s_setprio 1
	v_mfma_f32_16x16x32_bf16 v[52:55], v[160:163], v[184:187], 0
	v_mfma_f32_16x16x32_bf16 v[48:51], v[176:179], v[184:187], 0
	v_mfma_f32_16x16x32_bf16 v[36:39], v[160:163], v[192:195], 0
	v_mfma_f32_16x16x32_bf16 v[32:35], v[176:179], v[192:195], 0
	v_mfma_f32_16x16x32_bf16 v[20:23], v[160:163], v[206:209], 0
	v_mfma_f32_16x16x32_bf16 v[16:19], v[176:179], v[206:209], 0
	v_mfma_f32_16x16x32_bf16 v[4:7], v[160:163], v[214:217], 0
	v_mfma_f32_16x16x32_bf16 v[0:3], v[176:179], v[214:217], 0
	v_mfma_f32_16x16x32_bf16 v[52:55], v[164:167], v[188:191], v[52:55]
	v_mfma_f32_16x16x32_bf16 v[48:51], v[180:183], v[188:191], v[48:51]
	v_mfma_f32_16x16x32_bf16 v[36:39], v[164:167], v[198:201], v[36:39]
	v_mfma_f32_16x16x32_bf16 v[32:35], v[180:183], v[198:201], v[32:35]
	v_mfma_f32_16x16x32_bf16 v[20:23], v[164:167], v[210:213], v[20:23]
	v_mfma_f32_16x16x32_bf16 v[16:19], v[180:183], v[210:213], v[16:19]
	v_mfma_f32_16x16x32_bf16 v[4:7], v[164:167], v[218:221], v[4:7]
	v_mfma_f32_16x16x32_bf16 v[0:3], v[180:183], v[218:221], v[0:3]
	s_setprio 0
	s_barrier
	s_add_i32 s33, 0, 0x18000
	s_add_i32 s44, 0, 0x1c000
	v_add_u32_e32 v156, s33, v169
	v_add_u32_e32 v175, s44, v169
	ds_read_b128 v[128:131], v156
	ds_read_b128 v[132:135], v156 offset:1024
	ds_read_b128 v[136:139], v156 offset:2048
	ds_read_b128 v[156:159], v156 offset:3072
	ds_read_b128 v[160:163], v175
	ds_read_b128 v[164:167], v175 offset:1024
	ds_read_b128 v[176:179], v175 offset:2048
	ds_read_b128 v[180:183], v175 offset:3072
	s_add_u32 s18, s18, 0x40000
	s_addc_u32 s19, s19, 0
	s_mov_b32 m0, s85
	v_lshl_add_u64 v[230:231], s[18:19], 0, v[140:141]
	ds_read_b128 v[184:187], v173 offset:32768
	ds_read_b128 v[188:191], v173 offset:33792
	ds_read_b128 v[192:195], v173 offset:34816
	ds_read_b128 v[198:201], v173 offset:35840
	ds_read_b128 v[206:209], v173 offset:36864
	ds_read_b128 v[210:213], v173 offset:37888
	ds_read_b128 v[214:217], v173 offset:38912
	ds_read_b128 v[218:221], v173 offset:39936
	global_load_lds_dwordx4 v[230:231], off
	v_lshl_add_u64 v[230:231], s[18:19], 0, v[144:145]
	s_mov_b32 m0, s86
	s_nop 0
	global_load_lds_dwordx4 v[230:231], off
	s_waitcnt vmcnt(8)
	s_waitcnt lgkmcnt(0)
	s_barrier
	s_setprio 1
	s_waitcnt lgkmcnt(0)
	v_mfma_f32_16x16x32_bf16 v[124:127], v[128:131], v[184:187], v[124:127]
	v_mfma_f32_16x16x32_bf16 v[120:123], v[136:139], v[184:187], v[120:123]
	v_mfma_f32_16x16x32_bf16 v[108:111], v[128:131], v[192:195], v[108:111]
	v_mfma_f32_16x16x32_bf16 v[104:107], v[136:139], v[192:195], v[104:107]
	v_mfma_f32_16x16x32_bf16 v[92:95], v[128:131], v[206:209], v[92:95]
	v_mfma_f32_16x16x32_bf16 v[88:91], v[136:139], v[206:209], v[88:91]
	v_mfma_f32_16x16x32_bf16 v[76:79], v[128:131], v[214:217], v[76:79]
	v_mfma_f32_16x16x32_bf16 v[72:75], v[136:139], v[214:217], v[72:75]
	v_mfma_f32_16x16x32_bf16 v[124:127], v[132:135], v[188:191], v[124:127]
	v_mfma_f32_16x16x32_bf16 v[120:123], v[156:159], v[188:191], v[120:123]
	v_mfma_f32_16x16x32_bf16 v[108:111], v[132:135], v[198:201], v[108:111]
	v_mfma_f32_16x16x32_bf16 v[104:107], v[156:159], v[198:201], v[104:107]
	v_mfma_f32_16x16x32_bf16 v[92:95], v[132:135], v[210:213], v[92:95]
	v_mfma_f32_16x16x32_bf16 v[88:91], v[156:159], v[210:213], v[88:91]
	v_mfma_f32_16x16x32_bf16 v[76:79], v[132:135], v[218:221], v[76:79]
	v_mfma_f32_16x16x32_bf16 v[72:75], v[156:159], v[218:221], v[72:75]
	s_setprio 0
	s_setprio 1
	v_mfma_f32_16x16x32_bf16 v[116:119], v[160:163], v[184:187], v[116:119]
	v_mfma_f32_16x16x32_bf16 v[112:115], v[176:179], v[184:187], v[112:115]
	v_mfma_f32_16x16x32_bf16 v[100:103], v[160:163], v[192:195], v[100:103]
	v_mfma_f32_16x16x32_bf16 v[96:99], v[176:179], v[192:195], v[96:99]
	v_mfma_f32_16x16x32_bf16 v[84:87], v[160:163], v[206:209], v[84:87]
	v_mfma_f32_16x16x32_bf16 v[80:83], v[176:179], v[206:209], v[80:83]
	v_mfma_f32_16x16x32_bf16 v[68:71], v[160:163], v[214:217], v[68:71]
	v_mfma_f32_16x16x32_bf16 v[64:67], v[176:179], v[214:217], v[64:67]
	v_mfma_f32_16x16x32_bf16 v[116:119], v[164:167], v[188:191], v[116:119]
	v_mfma_f32_16x16x32_bf16 v[112:115], v[180:183], v[188:191], v[112:115]
	v_mfma_f32_16x16x32_bf16 v[100:103], v[164:167], v[198:201], v[100:103]
	v_mfma_f32_16x16x32_bf16 v[96:99], v[180:183], v[198:201], v[96:99]
	v_mfma_f32_16x16x32_bf16 v[84:87], v[164:167], v[210:213], v[84:87]
	v_mfma_f32_16x16x32_bf16 v[80:83], v[180:183], v[210:213], v[80:83]
	v_mfma_f32_16x16x32_bf16 v[68:71], v[164:167], v[218:221], v[68:71]
	v_mfma_f32_16x16x32_bf16 v[64:67], v[180:183], v[218:221], v[64:67]
	s_setprio 0
	s_barrier
	s_add_i32 s18, s33, s82
	v_lshl_add_u64 v[222:223], v[222:223], 0, s[68:69]
	s_mov_b32 m0, s18
	ds_read_b128 v[184:187], v173 offset:49152
	ds_read_b128 v[188:191], v173 offset:50176
	ds_read_b128 v[192:195], v173 offset:51200
	ds_read_b128 v[198:201], v173 offset:52224
	ds_read_b128 v[206:209], v173 offset:53248
	ds_read_b128 v[210:213], v173 offset:54272
	ds_read_b128 v[214:217], v173 offset:55296
	ds_read_b128 v[218:221], v173 offset:56320
	global_load_lds_dwordx4 v[222:223], off
	s_add_i32 m0, s18, 0x2000
	s_add_u32 s16, s16, 0x40080
	v_lshl_add_u64 v[222:223], v[224:225], 0, s[68:69]
	s_addc_u32 s17, s17, 0
	s_add_i32 s18, s44, s82
	global_load_lds_dwordx4 v[222:223], off
	v_lshl_add_u64 v[222:223], s[16:17], 0, v[142:143]
	s_mov_b32 m0, s18
	s_nop 0
	global_load_lds_dwordx4 v[222:223], off
	v_lshl_add_u64 v[222:223], s[16:17], 0, v[146:147]
	s_add_i32 m0, s18, 0x2000
	s_nop 0
	global_load_lds_dwordx4 v[222:223], off
	v_lshl_add_u64 v[222:223], v[226:227], 0, s[68:69]
	s_mov_b32 m0, s91
	s_nop 0
	global_load_lds_dwordx4 v[222:223], off
	v_lshl_add_u64 v[222:223], v[228:229], 0, s[68:69]
	s_mov_b32 m0, s92
	s_nop 0
	global_load_lds_dwordx4 v[222:223], off
	s_waitcnt vmcnt(8)
	s_waitcnt lgkmcnt(0)
	s_barrier
	s_setprio 1
	s_waitcnt lgkmcnt(0)
	v_mfma_f32_16x16x32_bf16 v[60:63], v[128:131], v[184:187], v[60:63]
	v_mfma_f32_16x16x32_bf16 v[56:59], v[136:139], v[184:187], v[56:59]
	v_mfma_f32_16x16x32_bf16 v[44:47], v[128:131], v[192:195], v[44:47]
	v_mfma_f32_16x16x32_bf16 v[40:43], v[136:139], v[192:195], v[40:43]
	v_mfma_f32_16x16x32_bf16 v[28:31], v[128:131], v[206:209], v[28:31]
	v_mfma_f32_16x16x32_bf16 v[24:27], v[136:139], v[206:209], v[24:27]
	v_mfma_f32_16x16x32_bf16 v[12:15], v[128:131], v[214:217], v[12:15]
	v_mfma_f32_16x16x32_bf16 v[8:11], v[136:139], v[214:217], v[8:11]
	v_mfma_f32_16x16x32_bf16 v[60:63], v[132:135], v[188:191], v[60:63]
	v_mfma_f32_16x16x32_bf16 v[56:59], v[156:159], v[188:191], v[56:59]
	v_mfma_f32_16x16x32_bf16 v[44:47], v[132:135], v[198:201], v[44:47]
	v_mfma_f32_16x16x32_bf16 v[40:43], v[156:159], v[198:201], v[40:43]
	v_mfma_f32_16x16x32_bf16 v[28:31], v[132:135], v[210:213], v[28:31]
	v_mfma_f32_16x16x32_bf16 v[24:27], v[156:159], v[210:213], v[24:27]
	v_mfma_f32_16x16x32_bf16 v[12:15], v[132:135], v[218:221], v[12:15]
	v_mfma_f32_16x16x32_bf16 v[8:11], v[156:159], v[218:221], v[8:11]
	s_setprio 0
	s_setprio 1
	v_mfma_f32_16x16x32_bf16 v[52:55], v[160:163], v[184:187], v[52:55]
	v_mfma_f32_16x16x32_bf16 v[48:51], v[176:179], v[184:187], v[48:51]
	v_mfma_f32_16x16x32_bf16 v[36:39], v[160:163], v[192:195], v[36:39]
	v_mfma_f32_16x16x32_bf16 v[32:35], v[176:179], v[192:195], v[32:35]
	v_mfma_f32_16x16x32_bf16 v[20:23], v[160:163], v[206:209], v[20:23]
	v_mfma_f32_16x16x32_bf16 v[16:19], v[176:179], v[206:209], v[16:19]
	v_mfma_f32_16x16x32_bf16 v[4:7], v[160:163], v[214:217], v[4:7]
	v_mfma_f32_16x16x32_bf16 v[0:3], v[176:179], v[214:217], v[0:3]
	v_mfma_f32_16x16x32_bf16 v[52:55], v[164:167], v[188:191], v[52:55]
	v_mfma_f32_16x16x32_bf16 v[48:51], v[180:183], v[188:191], v[48:51]
	v_mfma_f32_16x16x32_bf16 v[36:39], v[164:167], v[198:201], v[36:39]
	v_mfma_f32_16x16x32_bf16 v[32:35], v[180:183], v[198:201], v[32:35]
	v_mfma_f32_16x16x32_bf16 v[20:23], v[164:167], v[210:213], v[20:23]
	v_mfma_f32_16x16x32_bf16 v[16:19], v[180:183], v[210:213], v[16:19]
	v_mfma_f32_16x16x32_bf16 v[4:7], v[164:167], v[218:221], v[4:7]
	v_mfma_f32_16x16x32_bf16 v[0:3], v[180:183], v[218:221], v[0:3]
	s_setprio 0
	s_barrier
	s_add_i32 s57, s57, 2
	s_add_u32 s12, s12, 0x100
	s_addc_u32 s13, s13, 0
	s_add_u32 s14, s14, 0x100
	s_addc_u32 s15, s15, 0
	s_cmp_gt_u32 s57, 13
	s_branch .LBB0_259

.LBB0_757:
	s_ashr_i32 s21, s20, 31
	s_lshl_b64 s[22:23], s[20:21], 19
	s_add_u32 s22, s28, s22
	s_addc_u32 s23, s29, s23
	s_and_b64 s[24:25], s[0:1], exec
	s_cselect_b32 s21, s23, s39
	s_cselect_b32 s53, s22, s38
	s_ashr_i32 s19, s18, 31
	s_lshl_b64 s[24:25], s[18:19], 19
	s_add_u32 s24, s34, s24
	s_addc_u32 s25, s35, s25
	s_and_b64 s[42:43], s[0:1], exec
	s_cselect_b32 s19, s25, s41
	s_cselect_b32 s54, s24, s40
	s_add_u32 s38, s38, 0x40080
	s_addc_u32 s39, s39, 0
	s_add_u32 s55, s40, 0x100
	s_addc_u32 s56, s41, 0
	s_mov_b32 s57, -2
	ds_read_b128 v[144:147], v153
	ds_read_b128 v[156:159], v153 offset:1024
	ds_read_b128 v[160:163], v153 offset:2048
	ds_read_b128 v[164:167], v153 offset:3072
	ds_read_b128 v[168:171], v154
	ds_read_b128 v[172:175], v154 offset:1024
	ds_read_b128 v[176:179], v154 offset:2048
	ds_read_b128 v[180:183], v154 offset:3072
	s_add_u32 s40, s38, 0xfffc0080
	s_addc_u32 s41, s39, -1
	s_cmp_eq_u32 s57, 12
	s_cselect_b32 s43, s21, s41
	s_cselect_b32 s42, s53, s40
	s_cselect_b32 s41, s19, s56
	s_cselect_b32 s40, s54, s55
	v_lshl_add_u64 v[148:149], s[38:39], 0, v[136:137]
	s_add_i32 m0, s27, 0xc000
	ds_read_b128 v[184:187], v155
	ds_read_b128 v[188:191], v155 offset:1024
	ds_read_b128 v[192:195], v155 offset:2048
	ds_read_b128 v[196:199], v155 offset:3072
	ds_read_b128 v[200:203], v155 offset:4096
	ds_read_b128 v[204:207], v155 offset:5120
	ds_read_b128 v[208:211], v155 offset:6144
	ds_read_b128 v[212:215], v155 offset:7168
	global_load_lds_dwordx4 v[148:149], off
	v_lshl_add_u64 v[148:149], s[38:39], 0, v[138:139]
	s_add_i32 m0, s27, 0xe000
	s_nop 0
	global_load_lds_dwordx4 v[148:149], off
	s_waitcnt vmcnt(8)
	s_waitcnt lgkmcnt(0)
	s_barrier
	s_setprio 1
	s_waitcnt lgkmcnt(0)
	v_mfma_f32_16x16x32_bf16 v[124:127], v[144:147], v[184:187], 0
	v_mfma_f32_16x16x32_bf16 v[120:123], v[160:163], v[184:187], 0
	v_mfma_f32_16x16x32_bf16 v[108:111], v[144:147], v[192:195], 0
	v_mfma_f32_16x16x32_bf16 v[104:107], v[160:163], v[192:195], 0
	v_mfma_f32_16x16x32_bf16 v[92:95], v[144:147], v[200:203], 0
	v_mfma_f32_16x16x32_bf16 v[88:91], v[160:163], v[200:203], 0
	v_mfma_f32_16x16x32_bf16 v[76:79], v[144:147], v[208:211], 0
	v_mfma_f32_16x16x32_bf16 v[72:75], v[160:163], v[208:211], 0
	v_mfma_f32_16x16x32_bf16 v[124:127], v[156:159], v[188:191], v[124:127]
	v_mfma_f32_16x16x32_bf16 v[120:123], v[164:167], v[188:191], v[120:123]
	v_mfma_f32_16x16x32_bf16 v[108:111], v[156:159], v[196:199], v[108:111]
	v_mfma_f32_16x16x32_bf16 v[104:107], v[164:167], v[196:199], v[104:107]
	v_mfma_f32_16x16x32_bf16 v[92:95], v[156:159], v[204:207], v[92:95]
	v_mfma_f32_16x16x32_bf16 v[88:91], v[164:167], v[204:207], v[88:91]
	v_mfma_f32_16x16x32_bf16 v[76:79], v[156:159], v[212:215], v[76:79]
	v_mfma_f32_16x16x32_bf16 v[72:75], v[164:167], v[212:215], v[72:75]
	s_setprio 0
	s_setprio 1
	v_mfma_f32_16x16x32_bf16 v[116:119], v[168:171], v[184:187], 0
	v_mfma_f32_16x16x32_bf16 v[112:115], v[176:179], v[184:187], 0
	v_mfma_f32_16x16x32_bf16 v[100:103], v[168:171], v[192:195], 0
	v_mfma_f32_16x16x32_bf16 v[96:99], v[176:179], v[192:195], 0
	v_mfma_f32_16x16x32_bf16 v[84:87], v[168:171], v[200:203], 0
	v_mfma_f32_16x16x32_bf16 v[80:83], v[176:179], v[200:203], 0
	v_mfma_f32_16x16x32_bf16 v[68:71], v[168:171], v[208:211], 0
	v_mfma_f32_16x16x32_bf16 v[64:67], v[176:179], v[208:211], 0
	v_mfma_f32_16x16x32_bf16 v[116:119], v[172:175], v[188:191], v[116:119]
	v_mfma_f32_16x16x32_bf16 v[112:115], v[180:183], v[188:191], v[112:115]
	v_mfma_f32_16x16x32_bf16 v[100:103], v[172:175], v[196:199], v[100:103]
	v_mfma_f32_16x16x32_bf16 v[96:99], v[180:183], v[196:199], v[96:99]
	v_mfma_f32_16x16x32_bf16 v[84:87], v[172:175], v[204:207], v[84:87]
	v_mfma_f32_16x16x32_bf16 v[80:83], v[180:183], v[204:207], v[80:83]
	v_mfma_f32_16x16x32_bf16 v[68:71], v[172:175], v[212:215], v[68:71]
	v_mfma_f32_16x16x32_bf16 v[64:67], v[180:183], v[212:215], v[64:67]
	s_setprio 0
	s_barrier
	s_add_i32 s58, s50, s33
	v_lshl_add_u64 v[148:149], s[40:41], 0, v[130:131]
	s_mov_b32 m0, s58
	ds_read_b128 v[184:187], v155 offset:16384
	ds_read_b128 v[188:191], v155 offset:17408
	ds_read_b128 v[192:195], v155 offset:18432
	ds_read_b128 v[196:199], v155 offset:19456
	ds_read_b128 v[200:203], v155 offset:20480
	ds_read_b128 v[204:207], v155 offset:21504
	ds_read_b128 v[208:211], v155 offset:22528
	ds_read_b128 v[212:215], v155 offset:23552
	global_load_lds_dwordx4 v[148:149], off
	s_add_i32 m0, s58, 0x2000
	s_add_u32 s58, s40, 0x40000
	v_lshl_add_u64 v[216:217], s[40:41], 0, v[134:135]
	s_addc_u32 s59, s41, 0
	s_add_i32 s60, s51, s33
	global_load_lds_dwordx4 v[216:217], off
	v_lshl_add_u64 v[218:219], s[58:59], 0, v[130:131]
	s_mov_b32 m0, s60
	v_lshl_add_u64 v[220:221], s[42:43], 0, v[132:133]
	global_load_lds_dwordx4 v[218:219], off
	v_lshl_add_u64 v[218:219], s[58:59], 0, v[134:135]
	s_add_i32 m0, s60, 0x2000
	s_nop 0
	global_load_lds_dwordx4 v[218:219], off
	v_lshl_add_u64 v[218:219], s[42:43], 0, v[128:129]
	s_mov_b32 m0, s27
	s_nop 0
	global_load_lds_dwordx4 v[218:219], off
	s_mov_b32 m0, s44
	s_nop 0
	global_load_lds_dwordx4 v[220:221], off
	s_waitcnt vmcnt(8)
	s_waitcnt lgkmcnt(0)
	s_barrier
	s_setprio 1
	s_waitcnt lgkmcnt(0)
	v_mfma_f32_16x16x32_bf16 v[60:63], v[144:147], v[184:187], 0
	v_mfma_f32_16x16x32_bf16 v[56:59], v[160:163], v[184:187], 0
	v_mfma_f32_16x16x32_bf16 v[44:47], v[144:147], v[192:195], 0
	v_mfma_f32_16x16x32_bf16 v[40:43], v[160:163], v[192:195], 0
	v_mfma_f32_16x16x32_bf16 v[28:31], v[144:147], v[200:203], 0
	v_mfma_f32_16x16x32_bf16 v[24:27], v[160:163], v[200:203], 0
	v_mfma_f32_16x16x32_bf16 v[12:15], v[144:147], v[208:211], 0
	v_mfma_f32_16x16x32_bf16 v[8:11], v[160:163], v[208:211], 0
	v_mfma_f32_16x16x32_bf16 v[60:63], v[156:159], v[188:191], v[60:63]
	v_mfma_f32_16x16x32_bf16 v[56:59], v[164:167], v[188:191], v[56:59]
	v_mfma_f32_16x16x32_bf16 v[44:47], v[156:159], v[196:199], v[44:47]
	v_mfma_f32_16x16x32_bf16 v[40:43], v[164:167], v[196:199], v[40:43]
	v_mfma_f32_16x16x32_bf16 v[28:31], v[156:159], v[204:207], v[28:31]
	v_mfma_f32_16x16x32_bf16 v[24:27], v[164:167], v[204:207], v[24:27]
	v_mfma_f32_16x16x32_bf16 v[12:15], v[156:159], v[212:215], v[12:15]
	v_mfma_f32_16x16x32_bf16 v[8:11], v[164:167], v[212:215], v[8:11]
	s_setprio 0
	s_setprio 1
	v_mfma_f32_16x16x32_bf16 v[52:55], v[168:171], v[184:187], 0
	v_mfma_f32_16x16x32_bf16 v[48:51], v[176:179], v[184:187], 0
	v_mfma_f32_16x16x32_bf16 v[36:39], v[168:171], v[192:195], 0
	v_mfma_f32_16x16x32_bf16 v[32:35], v[176:179], v[192:195], 0
	v_mfma_f32_16x16x32_bf16 v[20:23], v[168:171], v[200:203], 0
	v_mfma_f32_16x16x32_bf16 v[16:19], v[176:179], v[200:203], 0
	v_mfma_f32_16x16x32_bf16 v[4:7], v[168:171], v[208:211], 0
	v_mfma_f32_16x16x32_bf16 v[0:3], v[176:179], v[208:211], 0
	v_mfma_f32_16x16x32_bf16 v[52:55], v[172:175], v[188:191], v[52:55]
	v_mfma_f32_16x16x32_bf16 v[48:51], v[180:183], v[188:191], v[48:51]
	v_mfma_f32_16x16x32_bf16 v[36:39], v[172:175], v[196:199], v[36:39]
	v_mfma_f32_16x16x32_bf16 v[32:35], v[180:183], v[196:199], v[32:35]
	v_mfma_f32_16x16x32_bf16 v[20:23], v[172:175], v[204:207], v[20:23]
	v_mfma_f32_16x16x32_bf16 v[16:19], v[180:183], v[204:207], v[16:19]
	v_mfma_f32_16x16x32_bf16 v[4:7], v[172:175], v[212:215], v[4:7]
	v_mfma_f32_16x16x32_bf16 v[0:3], v[180:183], v[212:215], v[0:3]
	s_setprio 0
	s_barrier
	s_add_i32 s58, 0, 0x18000
	s_add_i32 s59, 0, 0x1c000
	v_add_u32_e32 v164, s58, v151
	v_add_u32_e32 v180, s59, v151
	ds_read_b128 v[144:147], v164
	ds_read_b128 v[156:159], v164 offset:1024
	ds_read_b128 v[160:163], v164 offset:2048
	ds_read_b128 v[164:167], v164 offset:3072
	ds_read_b128 v[168:171], v180
	ds_read_b128 v[172:175], v180 offset:1024
	ds_read_b128 v[176:179], v180 offset:2048
	ds_read_b128 v[180:183], v180 offset:3072
	s_add_u32 s42, s42, 0x40000
	s_addc_u32 s43, s43, 0
	s_mov_b32 m0, s45
	v_lshl_add_u64 v[222:223], s[42:43], 0, v[128:129]
	ds_read_b128 v[184:187], v155 offset:32768
	ds_read_b128 v[188:191], v155 offset:33792
	ds_read_b128 v[192:195], v155 offset:34816
	ds_read_b128 v[196:199], v155 offset:35840
	ds_read_b128 v[200:203], v155 offset:36864
	ds_read_b128 v[204:207], v155 offset:37888
	ds_read_b128 v[208:211], v155 offset:38912
	ds_read_b128 v[212:215], v155 offset:39936
	global_load_lds_dwordx4 v[222:223], off
	v_lshl_add_u64 v[222:223], s[42:43], 0, v[132:133]
	s_mov_b32 m0, s46
	s_nop 0
	global_load_lds_dwordx4 v[222:223], off
	s_waitcnt vmcnt(8)
	s_waitcnt lgkmcnt(0)
	s_barrier
	s_setprio 1
	s_waitcnt lgkmcnt(0)
	v_mfma_f32_16x16x32_bf16 v[124:127], v[144:147], v[184:187], v[124:127]
	v_mfma_f32_16x16x32_bf16 v[120:123], v[160:163], v[184:187], v[120:123]
	v_mfma_f32_16x16x32_bf16 v[108:111], v[144:147], v[192:195], v[108:111]
	v_mfma_f32_16x16x32_bf16 v[104:107], v[160:163], v[192:195], v[104:107]
	v_mfma_f32_16x16x32_bf16 v[92:95], v[144:147], v[200:203], v[92:95]
	v_mfma_f32_16x16x32_bf16 v[88:91], v[160:163], v[200:203], v[88:91]
	v_mfma_f32_16x16x32_bf16 v[76:79], v[144:147], v[208:211], v[76:79]
	v_mfma_f32_16x16x32_bf16 v[72:75], v[160:163], v[208:211], v[72:75]
	v_mfma_f32_16x16x32_bf16 v[124:127], v[156:159], v[188:191], v[124:127]
	v_mfma_f32_16x16x32_bf16 v[120:123], v[164:167], v[188:191], v[120:123]
	v_mfma_f32_16x16x32_bf16 v[108:111], v[156:159], v[196:199], v[108:111]
	v_mfma_f32_16x16x32_bf16 v[104:107], v[164:167], v[196:199], v[104:107]
	v_mfma_f32_16x16x32_bf16 v[92:95], v[156:159], v[204:207], v[92:95]
	v_mfma_f32_16x16x32_bf16 v[88:91], v[164:167], v[204:207], v[88:91]
	v_mfma_f32_16x16x32_bf16 v[76:79], v[156:159], v[212:215], v[76:79]
	v_mfma_f32_16x16x32_bf16 v[72:75], v[164:167], v[212:215], v[72:75]
	s_setprio 0
	s_setprio 1
	v_mfma_f32_16x16x32_bf16 v[116:119], v[168:171], v[184:187], v[116:119]
	v_mfma_f32_16x16x32_bf16 v[112:115], v[176:179], v[184:187], v[112:115]
	v_mfma_f32_16x16x32_bf16 v[100:103], v[168:171], v[192:195], v[100:103]
	v_mfma_f32_16x16x32_bf16 v[96:99], v[176:179], v[192:195], v[96:99]
	v_mfma_f32_16x16x32_bf16 v[84:87], v[168:171], v[200:203], v[84:87]
	v_mfma_f32_16x16x32_bf16 v[80:83], v[176:179], v[200:203], v[80:83]
	v_mfma_f32_16x16x32_bf16 v[68:71], v[168:171], v[208:211], v[68:71]
	v_mfma_f32_16x16x32_bf16 v[64:67], v[176:179], v[208:211], v[64:67]
	v_mfma_f32_16x16x32_bf16 v[116:119], v[172:175], v[188:191], v[116:119]
	v_mfma_f32_16x16x32_bf16 v[112:115], v[180:183], v[188:191], v[112:115]
	v_mfma_f32_16x16x32_bf16 v[100:103], v[172:175], v[196:199], v[100:103]
	v_mfma_f32_16x16x32_bf16 v[96:99], v[180:183], v[196:199], v[96:99]
	v_mfma_f32_16x16x32_bf16 v[84:87], v[172:175], v[204:207], v[84:87]
	v_mfma_f32_16x16x32_bf16 v[80:83], v[180:183], v[204:207], v[80:83]
	v_mfma_f32_16x16x32_bf16 v[68:71], v[172:175], v[212:215], v[68:71]
	v_mfma_f32_16x16x32_bf16 v[64:67], v[180:183], v[212:215], v[64:67]
	s_setprio 0
	s_barrier
	s_add_i32 s42, s58, s33
	v_lshl_add_u64 v[148:149], v[148:149], 0, s[6:7]
	s_mov_b32 m0, s42
	ds_read_b128 v[184:187], v155 offset:49152
	ds_read_b128 v[188:191], v155 offset:50176
	ds_read_b128 v[192:195], v155 offset:51200
	ds_read_b128 v[196:199], v155 offset:52224
	ds_read_b128 v[200:203], v155 offset:53248
	ds_read_b128 v[204:207], v155 offset:54272
	ds_read_b128 v[208:211], v155 offset:55296
	ds_read_b128 v[212:215], v155 offset:56320
	global_load_lds_dwordx4 v[148:149], off
	s_add_i32 m0, s42, 0x2000
	s_add_u32 s40, s40, 0x40080
	v_lshl_add_u64 v[148:149], v[216:217], 0, s[6:7]
	s_addc_u32 s41, s41, 0
	s_add_i32 s42, s59, s33
	global_load_lds_dwordx4 v[148:149], off
	v_lshl_add_u64 v[148:149], s[40:41], 0, v[130:131]
	s_mov_b32 m0, s42
	s_nop 0
	global_load_lds_dwordx4 v[148:149], off
	v_lshl_add_u64 v[148:149], s[40:41], 0, v[134:135]
	s_add_i32 m0, s42, 0x2000
	s_nop 0
	global_load_lds_dwordx4 v[148:149], off
	v_lshl_add_u64 v[148:149], v[218:219], 0, s[6:7]
	s_mov_b32 m0, s48
	s_nop 0
	global_load_lds_dwordx4 v[148:149], off
	v_lshl_add_u64 v[148:149], v[220:221], 0, s[6:7]
	s_mov_b32 m0, s49
	s_nop 0
	global_load_lds_dwordx4 v[148:149], off
	s_waitcnt vmcnt(8)
	s_waitcnt lgkmcnt(0)
	s_barrier
	s_setprio 1
	s_waitcnt lgkmcnt(0)
	v_mfma_f32_16x16x32_bf16 v[60:63], v[144:147], v[184:187], v[60:63]
	v_mfma_f32_16x16x32_bf16 v[56:59], v[160:163], v[184:187], v[56:59]
	v_mfma_f32_16x16x32_bf16 v[44:47], v[144:147], v[192:195], v[44:47]
	v_mfma_f32_16x16x32_bf16 v[40:43], v[160:163], v[192:195], v[40:43]
	v_mfma_f32_16x16x32_bf16 v[28:31], v[144:147], v[200:203], v[28:31]
	v_mfma_f32_16x16x32_bf16 v[24:27], v[160:163], v[200:203], v[24:27]
	v_mfma_f32_16x16x32_bf16 v[12:15], v[144:147], v[208:211], v[12:15]
	v_mfma_f32_16x16x32_bf16 v[8:11], v[160:163], v[208:211], v[8:11]
	v_mfma_f32_16x16x32_bf16 v[60:63], v[156:159], v[188:191], v[60:63]
	v_mfma_f32_16x16x32_bf16 v[56:59], v[164:167], v[188:191], v[56:59]
	v_mfma_f32_16x16x32_bf16 v[44:47], v[156:159], v[196:199], v[44:47]
	v_mfma_f32_16x16x32_bf16 v[40:43], v[164:167], v[196:199], v[40:43]
	v_mfma_f32_16x16x32_bf16 v[28:31], v[156:159], v[204:207], v[28:31]
	v_mfma_f32_16x16x32_bf16 v[24:27], v[164:167], v[204:207], v[24:27]
	v_mfma_f32_16x16x32_bf16 v[12:15], v[156:159], v[212:215], v[12:15]
	v_mfma_f32_16x16x32_bf16 v[8:11], v[164:167], v[212:215], v[8:11]
	s_setprio 0
	s_setprio 1
	v_mfma_f32_16x16x32_bf16 v[52:55], v[168:171], v[184:187], v[52:55]
	v_mfma_f32_16x16x32_bf16 v[48:51], v[176:179], v[184:187], v[48:51]
	v_mfma_f32_16x16x32_bf16 v[36:39], v[168:171], v[192:195], v[36:39]
	v_mfma_f32_16x16x32_bf16 v[32:35], v[176:179], v[192:195], v[32:35]
	v_mfma_f32_16x16x32_bf16 v[20:23], v[168:171], v[200:203], v[20:23]
	v_mfma_f32_16x16x32_bf16 v[16:19], v[176:179], v[200:203], v[16:19]
	v_mfma_f32_16x16x32_bf16 v[4:7], v[168:171], v[208:211], v[4:7]
	v_mfma_f32_16x16x32_bf16 v[0:3], v[176:179], v[208:211], v[0:3]
	v_mfma_f32_16x16x32_bf16 v[52:55], v[172:175], v[188:191], v[52:55]
	v_mfma_f32_16x16x32_bf16 v[48:51], v[180:183], v[188:191], v[48:51]
	v_mfma_f32_16x16x32_bf16 v[36:39], v[172:175], v[196:199], v[36:39]
	v_mfma_f32_16x16x32_bf16 v[32:35], v[180:183], v[196:199], v[32:35]
	v_mfma_f32_16x16x32_bf16 v[20:23], v[172:175], v[204:207], v[20:23]
	v_mfma_f32_16x16x32_bf16 v[16:19], v[180:183], v[204:207], v[16:19]
	v_mfma_f32_16x16x32_bf16 v[4:7], v[172:175], v[212:215], v[4:7]
	v_mfma_f32_16x16x32_bf16 v[0:3], v[180:183], v[212:215], v[0:3]
	s_setprio 0
	s_barrier
	s_add_i32 s57, s57, 2
	s_add_u32 s38, s38, 0x100
	s_addc_u32 s39, s39, 0
	s_add_u32 s55, s55, 0x100
	s_addc_u32 s56, s56, 0
	s_cmp_gt_u32 s57, 13
	s_branch .LBB0_758
